# mix phase: blocks>=256 run retout, attention, retout (was attention, retout, retout); modulate param loads hoisted, row 1 reuses row 0 params
# speedup vs baseline: 1.1291x; 1.0128x over previous
.LBB0_17:
	s_and_b64 vcc, exec, s[84:85]
	v_writelane_b32 v253, s3, 14
	s_cbranch_vccz .LBB0_23
	s_mul_hi_u32 s0, s3, 0xaaaaaaab
	s_lshr_b32 s2, s0, 2
	s_mul_i32 s8, s2, s81
	s_add_i32 s8, s8, s88
	s_cmpk_lt_i32 s8, 0x100
	s_cselect_b64 s[0:1], -1, 0
	s_cmpk_gt_i32 s8, 0xff
	s_cbranch_scc1 .LBB0_105
	s_mul_i32 s9, s2, -6
	s_add_i32 s9, s9, s3
	s_add_i32 s9, s9, 3
	s_cmp_gt_u32 s9, 5
	s_cselect_b32 s4, 6, 0
	s_sub_i32 s9, s9, s4
	s_cmp_lt_i32 s9, 1
	s_cbranch_scc1 .LBB0_106
	s_cmp_eq_u32 s9, 1
	s_mov_b64 s[4:5], -1
	s_cbranch_scc0 .LBB0_22
	s_add_i32 s2, s8, 0xffffff80
	s_cmp_lt_u32 s2, 0x80
	v_readlane_b32 s4, v252, 46
	s_cselect_b64 s[2:3], -1, 0
	v_readlane_b32 s5, v252, 47
	s_and_b64 s[2:3], s[4:5], s[2:3]
	s_and_b64 s[2:3], s[2:3], exec
	s_cselect_b32 s3, 2, -1
	s_cselect_b32 s2, s8, 0
	s_mov_b64 s[4:5], 0

.LBB0_896:
	v_lshl_add_u64 v[30:31], s[2:3], 0, v[0:1]
	flat_load_dwordx4 v[22:25], v[30:31] offset:2048
	flat_load_dwordx4 v[18:21], v[30:31] offset:2064
	flat_load_dwordx4 v[26:29], v[30:31] offset:16
	s_nop 0
	flat_load_dwordx4 v[30:33], v[30:31]
	s_add_u32 s2, s8, s17
	s_addc_u32 s3, s9, s16
	s_mul_hi_u32 s8, s2, 0x3000
	s_mulk_i32 s3, 0x3000
	s_mulk_i32 s2, 0x3000
	s_add_i32 s3, s8, s3
	s_add_u32 s8, s28, s2
	s_addc_u32 s9, s29, s3
	s_lshl_b64 s[2:3], s[6:7], 11
	s_add_u32 s6, s96, s2
	s_addc_u32 s7, s97, s3
	s_add_u32 s0, s0, s17
	s_addc_u32 s2, s1, s16
	s_mul_hi_u32 s3, s0, 0x3000
	s_mulk_i32 s2, 0x3000
	s_mul_i32 s12, s0, 0x3000
	s_lshl_b64 s[0:1], s[10:11], 11
	s_add_i32 s3, s3, s2
	s_add_u32 s0, s96, s0
	s_addc_u32 s1, s97, s1
	s_add_u32 s2, s28, s12
	v_and_b32_e32 v35, 64, v207
	s_addc_u32 s3, s29, s3
	s_add_u32 s10, s8, 0x1000
	s_addc_u32 s11, s9, 0
	v_or_b32_e32 v98, 0x800, v0
	global_load_dwordx4 v[36:39], v0, s[4:5] offset:16
	global_load_dwordx4 v[40:43], v0, s[4:5]
	global_load_dwordx4 v[44:47], v0, s[4:5] offset:2064
	global_load_dwordx4 v[48:51], v0, s[4:5] offset:2048
	global_load_dwordx4 v[52:55], v0, s[10:11] offset:16
	global_load_dwordx4 v[56:59], v0, s[10:11]
	global_load_dwordx4 v[60:63], v98, s[10:11] offset:16
	global_load_dwordx4 v[64:67], v98, s[10:11]
	global_load_dwordx4 v[68:71], v0, s[8:9] offset:16
	global_load_dwordx4 v[72:75], v0, s[8:9]
	global_load_dwordx4 v[76:79], v0, s[8:9] offset:2064
	global_load_dwordx4 v[80:83], v0, s[8:9] offset:2048
	s_waitcnt vmcnt(12) lgkmcnt(0)
	v_mov_b32_e32 v124, v15
	v_mov_b32_e32 v125, v11
	v_mov_b32_e32 v128, v7
	v_mov_b32_e32 v129, v3
	v_xor_b32_e32 v134, 1, v207
	v_add_u32_e32 v35, 64, v35
	v_mov_b32_e32 v122, v14
	v_mov_b32_e32 v123, v10
	v_mov_b32_e32 v126, v6
	v_mov_b32_e32 v127, v2
	v_xor_b32_e32 v135, 2, v207
	v_pk_mul_f32 v[124:125], v[124:125], v[124:125]
	v_pk_mul_f32 v[128:129], v[128:129], v[128:129]
	v_cmp_lt_i32_e32 vcc, v134, v35
	v_mov_b32_e32 v130, v16
	v_mov_b32_e32 v131, v12
	v_mov_b32_e32 v140, v8
	v_mov_b32_e32 v141, v4
	v_pk_fma_f32 v[132:133], v[122:123], v[122:123], v[124:125]
	v_pk_fma_f32 v[144:145], v[126:127], v[126:127], v[128:129]
	v_cndmask_b32_e32 v148, v207, v134, vcc
	v_cmp_lt_i32_e32 vcc, v135, v35
	v_mov_b32_e32 v138, v17
	v_mov_b32_e32 v139, v13
	v_mov_b32_e32 v142, v9
	v_mov_b32_e32 v143, v5
	v_cndmask_b32_e32 v149, v207, v135, vcc
	v_pk_fma_f32 v[146:147], v[130:131], v[130:131], v[132:133]
	v_pk_fma_f32 v[140:141], v[140:141], v[140:141], v[144:145]
	v_lshlrev_b32_e32 v99, 2, v148
	v_lshlrev_b32_e32 v100, 2, v149
	v_pk_fma_f32 v[84:85], v[138:139], v[138:139], v[146:147]
	v_pk_fma_f32 v[86:87], v[142:143], v[142:143], v[140:141]
	s_mov_b32 s8, 0x3a800000
	s_mov_b32 s10, 0x800000
	v_mov_b32_e32 v94, v23
	v_mov_b32_e32 v95, v19
	v_mov_b32_e32 v92, v22
	v_mov_b32_e32 v93, v18
	v_pk_mul_f32 v[94:95], v[94:95], v[94:95]
	v_mov_b32_e32 v88, v24
	v_mov_b32_e32 v89, v20
	v_pk_fma_f32 v[92:93], v[92:93], v[92:93], v[94:95]
	v_mov_b32_e32 v96, v31
	v_mov_b32_e32 v97, v27
	v_mov_b32_e32 v90, v25
	v_mov_b32_e32 v91, v21
	v_pk_fma_f32 v[88:89], v[88:89], v[88:89], v[92:93]
	v_mov_b32_e32 v94, v30
	v_mov_b32_e32 v95, v26
	v_pk_mul_f32 v[96:97], v[96:97], v[96:97]
	v_pk_fma_f32 v[88:89], v[90:91], v[90:91], v[88:89]
	v_mov_b32_e32 v90, v32
	v_mov_b32_e32 v91, v28
	v_pk_fma_f32 v[94:95], v[94:95], v[94:95], v[96:97]
	v_mov_b32_e32 v92, v33
	v_mov_b32_e32 v93, v29
	v_pk_fma_f32 v[90:91], v[90:91], v[90:91], v[94:95]
	s_waitcnt vmcnt(7)
	v_pk_add_f32 v[52:53], v[52:53], 1.0 op_sel_hi:[1,0]
	v_pk_fma_f32 v[90:91], v[92:93], v[92:93], v[90:91]
	v_mov_b32_e32 v93, v84
	v_mov_b32_e32 v92, v90
	v_mov_b32_e32 v84, v91
	v_pk_add_f32 v[84:85], v[92:93], v[84:85]
	v_mov_b32_e32 v90, v88
	v_mov_b32_e32 v91, v86
	v_pk_add_f32 v[84:85], v[84:85], v[90:91]
	v_mov_b32_e32 v86, v89
	v_pk_add_f32 v[84:85], v[84:85], v[86:87]
	ds_bpermute_b32 v87, v99, v85
	ds_bpermute_b32 v86, v99, v84
	v_xor_b32_e32 v88, 4, v207
	v_cmp_lt_i32_e32 vcc, v88, v35
	v_xor_b32_e32 v89, 8, v207
	s_waitcnt vmcnt(6)
	v_pk_add_f32 v[56:57], v[56:57], 1.0 op_sel_hi:[1,0]
	s_waitcnt lgkmcnt(0)
	v_pk_add_f32 v[84:85], v[84:85], v[86:87]
	ds_bpermute_b32 v87, v100, v85
	ds_bpermute_b32 v86, v100, v84
	v_cndmask_b32_e32 v88, v207, v88, vcc
	v_lshlrev_b32_e32 v88, 2, v88
	v_cmp_lt_i32_e32 vcc, v89, v35
	v_pk_add_f32 v[58:59], v[58:59], 1.0 op_sel_hi:[1,0]
	s_waitcnt lgkmcnt(0)
	v_pk_add_f32 v[84:85], v[84:85], v[86:87]
	ds_bpermute_b32 v87, v88, v85
	ds_bpermute_b32 v86, v88, v84
	v_cndmask_b32_e32 v89, v207, v89, vcc
	v_lshlrev_b32_e32 v89, 2, v89
	v_xor_b32_e32 v88, 16, v207
	v_cmp_lt_i32_e32 vcc, v88, v35
	s_waitcnt lgkmcnt(0)
	v_pk_add_f32 v[84:85], v[84:85], v[86:87]
	ds_bpermute_b32 v87, v89, v85
	ds_bpermute_b32 v86, v89, v84
	v_cndmask_b32_e32 v88, v207, v88, vcc
	v_lshlrev_b32_e32 v88, 2, v88
	v_xor_b32_e32 v89, 32, v207
	v_cmp_lt_i32_e32 vcc, v89, v35
	s_waitcnt lgkmcnt(0)
	v_pk_add_f32 v[84:85], v[84:85], v[86:87]
	ds_bpermute_b32 v87, v88, v85
	ds_bpermute_b32 v86, v88, v84
	v_cndmask_b32_e32 v35, v207, v89, vcc
	v_lshlrev_b32_e32 v35, 2, v35
	v_pk_add_f32 v[54:55], v[54:55], 1.0 op_sel_hi:[1,0]
	s_waitcnt vmcnt(4)
	v_pk_add_f32 v[64:65], v[64:65], 1.0 op_sel_hi:[1,0]
	s_waitcnt lgkmcnt(0)
	v_pk_add_f32 v[84:85], v[84:85], v[86:87]
	ds_bpermute_b32 v87, v35, v85
	ds_bpermute_b32 v86, v35, v84
	v_pk_add_f32 v[66:67], v[66:67], 1.0 op_sel_hi:[1,0]
	v_pk_add_f32 v[60:61], v[60:61], 1.0 op_sel_hi:[1,0]
	v_pk_add_f32 v[62:63], v[62:63], 1.0 op_sel_hi:[1,0]
	s_waitcnt lgkmcnt(0)
	v_pk_add_f32 v[84:85], v[84:85], v[86:87]
	s_nop 0
	v_pk_fma_f32 v[84:85], v[84:85], s[8:9], v[240:241] op_sel_hi:[1,0,0]
	s_add_u32 s8, s2, 0x1000
	v_mul_f32_e32 v35, 0x4b800000, v85
	v_cmp_gt_f32_e32 vcc, s10, v85
	s_addc_u32 s9, s3, 0
	s_add_i32 s23, s23, s80
	v_cndmask_b32_e32 v35, v85, v35, vcc
	v_rsq_f32_e32 v35, v35
	v_lshlrev_b32_e32 v85, 1, v34
	v_mul_f32_e32 v34, 0x45800000, v35
	v_cndmask_b32_e32 v34, v35, v34, vcc
	v_pk_mul_f32 v[14:15], v[14:15], v[34:35] op_sel_hi:[1,0]
	v_pk_mul_f32 v[16:17], v[16:17], v[34:35] op_sel_hi:[1,0]
	v_pk_mul_f32 v[10:11], v[10:11], v[34:35] op_sel_hi:[1,0]
	v_pk_mul_f32 v[12:13], v[12:13], v[34:35] op_sel_hi:[1,0]
	v_pk_mul_f32 v[14:15], v[40:41], v[14:15]
	v_pk_mul_f32 v[16:17], v[42:43], v[16:17]
	v_pk_mul_f32 v[10:11], v[10:11], v[36:37]
	v_pk_mul_f32 v[12:13], v[12:13], v[38:39]
	v_pk_mul_f32 v[6:7], v[6:7], v[34:35] op_sel_hi:[1,0]
	v_pk_mul_f32 v[8:9], v[8:9], v[34:35] op_sel_hi:[1,0]
	v_pk_mul_f32 v[2:3], v[2:3], v[34:35] op_sel_hi:[1,0]
	v_pk_mul_f32 v[4:5], v[4:5], v[34:35] op_sel_hi:[1,0]
	s_waitcnt vmcnt(2)
	v_pk_fma_f32 v[14:15], v[56:57], v[14:15], v[72:73]
	v_pk_fma_f32 v[16:17], v[58:59], v[16:17], v[74:75]
	v_pk_fma_f32 v[10:11], v[10:11], v[52:53], v[68:69]
	v_pk_fma_f32 v[12:13], v[12:13], v[54:55], v[70:71]
	v_pk_mul_f32 v[6:7], v[6:7], v[48:49]
	v_pk_mul_f32 v[8:9], v[8:9], v[50:51]
	v_pk_mul_f32 v[2:3], v[2:3], v[44:45]
	v_pk_mul_f32 v[4:5], v[4:5], v[46:47]
	v_cvt_pk_bf16_f32 v14, v14, v15
	v_cvt_pk_bf16_f32 v15, v16, v17
	v_cvt_pk_bf16_f32 v16, v10, v11
	v_cvt_pk_bf16_f32 v17, v12, v13
	s_waitcnt vmcnt(0)
	v_pk_fma_f32 v[6:7], v[6:7], v[64:65], v[80:81]
	v_pk_fma_f32 v[8:9], v[8:9], v[66:67], v[82:83]
	v_pk_fma_f32 v[2:3], v[2:3], v[60:61], v[76:77]
	v_pk_fma_f32 v[4:5], v[4:5], v[62:63], v[78:79]
	v_cvt_pk_bf16_f32 v6, v6, v7
	v_cvt_pk_bf16_f32 v7, v8, v9
	v_cvt_pk_bf16_f32 v8, v2, v3
	v_cvt_pk_bf16_f32 v9, v4, v5
	global_store_dwordx4 v85, v[14:17], s[6:7]
	global_store_dwordx4 v85, v[6:9], s[6:7] offset:1024
	v_mul_f32_e32 v0, 0x4b800000, v84
	v_cmp_gt_f32_e32 vcc, s10, v84
	v_readlane_b32 s2, v251, 42
	s_add_i32 s22, s22, s2
	v_cndmask_b32_e32 v0, v84, v0, vcc
	v_rsq_f32_e32 v0, v0
	s_cmpk_gt_i32 s23, 0x8ff
	v_mul_f32_e32 v86, 0x45800000, v0
	v_cndmask_b32_e32 v0, v0, v86, vcc
	v_pk_mul_f32 v[30:31], v[30:31], v[0:1] op_sel_hi:[1,0]
	v_pk_mul_f32 v[30:31], v[40:41], v[30:31]
	v_pk_fma_f32 v[30:31], v[56:57], v[30:31], v[72:73]
	v_pk_mul_f32 v[32:33], v[32:33], v[0:1] op_sel_hi:[1,0]
	v_pk_mul_f32 v[32:33], v[42:43], v[32:33]
	v_pk_fma_f32 v[32:33], v[58:59], v[32:33], v[74:75]
	v_pk_mul_f32 v[26:27], v[26:27], v[0:1] op_sel_hi:[1,0]
	v_pk_mul_f32 v[26:27], v[36:37], v[26:27]
	v_pk_fma_f32 v[26:27], v[52:53], v[26:27], v[68:69]
	v_pk_mul_f32 v[28:29], v[28:29], v[0:1] op_sel_hi:[1,0]
	v_pk_mul_f32 v[28:29], v[38:39], v[28:29]
	v_pk_fma_f32 v[28:29], v[54:55], v[28:29], v[70:71]
	v_cvt_pk_bf16_f32 v2, v30, v31
	v_cvt_pk_bf16_f32 v3, v32, v33
	v_cvt_pk_bf16_f32 v4, v26, v27
	v_cvt_pk_bf16_f32 v5, v28, v29
	global_store_dwordx4 v85, v[2:5], s[0:1]
	v_pk_mul_f32 v[22:23], v[22:23], v[0:1] op_sel_hi:[1,0]
	v_pk_mul_f32 v[22:23], v[48:49], v[22:23]
	v_pk_fma_f32 v[22:23], v[64:65], v[22:23], v[80:81]
	v_pk_mul_f32 v[24:25], v[24:25], v[0:1] op_sel_hi:[1,0]
	v_pk_mul_f32 v[24:25], v[50:51], v[24:25]
	v_pk_fma_f32 v[24:25], v[66:67], v[24:25], v[82:83]
	v_pk_mul_f32 v[18:19], v[18:19], v[0:1] op_sel_hi:[1,0]
	v_pk_mul_f32 v[18:19], v[44:45], v[18:19]
	v_pk_fma_f32 v[18:19], v[60:61], v[18:19], v[76:77]
	v_pk_mul_f32 v[20:21], v[20:21], v[0:1] op_sel_hi:[1,0]
	v_pk_mul_f32 v[20:21], v[46:47], v[20:21]
	v_pk_fma_f32 v[20:21], v[62:63], v[20:21], v[78:79]
	v_cvt_pk_bf16_f32 v6, v22, v23
	v_cvt_pk_bf16_f32 v7, v24, v25
	v_cvt_pk_bf16_f32 v8, v18, v19
	v_cvt_pk_bf16_f32 v9, v20, v21
	global_store_dwordx4 v85, v[6:9], s[0:1] offset:1024
	s_cbranch_scc1 .LBB0_757
